# RG-LRU (both modes): conv-tile staging loads de-serialized (16 loads in flight, one vmcnt wait, then LDS writes)
# baseline (speedup 1.0000x reference)
; DI int get_tid() { int t = threadIdx.x; asm volatile("" : "+v"(t)); return t; }
; DI float bf2f(u16 v) { return __uint_as_float(((unsigned)v) << 16); }
; DI void lru_job(const Params& P, int layer, int b, int chunk, int blk, int mode, char* smem, const LruConst& C) {
;     ...
;   const int tid = get_tid(), d = tid & 63, tq = tid >> 6;
;   const int seg_lo = chunk < 4 ? 0 : CTX, seg_hi = chunk < 4 ? CTX : TB, p0 = chunk * 64;
;   const int ch = blk * 64 + d;
;   const u16* XA = (const u16*)(P.ws + OFF_XA);
;   const int lane = tid & 63, r = lane & 31, h = lane >> 5, wdir = tq >> 1, wmi = tq & 1;
;   __syncthreads();
; #pragma unroll
;   for (int it = 0; it < 17; ++it) {
;     int idx = tid + it * 256;
;     int rr = idx >> 6, dd = idx & 63, pp = p0 - 1 + rr;
;     if (idx < 67 * 64) xs[idx] = (pp >= seg_lo && pp < seg_hi) ? bf2f(XA[((size_t)b * TB + pp) * 512 + blk * 64 + dd]) : 0.f;
;   }
.LBB0_711:
	s_mul_hi_i32 s8, s22, 0x78787879
	s_lshr_b32 s9, s8, 31
	s_ashr_i32 s14, s8, 8
	s_add_i32 s14, s14, s9
	s_and_b64 s[8:9], s[6:7], exec
	s_movk_i32 s8, 0x100
	s_cselect_b32 s15, 0, 0x100
	s_cselect_b32 s16, s8, 0x1100
	s_lshl_b32 s25, s24, 6
	v_mov_b32_e32 v145, v171
	s_add_i32 s17, s25, -1
	s_lshl_b64 s[8:9], s[4:5], 1
	v_readlane_b32 s12, v251, 18
	v_readlane_b32 s13, v251, 19
	v_and_b32_e32 v144, 63, v145
	s_add_u32 s8, s12, s8
	s_addc_u32 s9, s13, s9
	v_lshlrev_b32_e32 v0, 1, v144
	v_mov_b32_e32 v1, v169
	v_lshl_add_u64 v[2:3], s[8:9], 0, v[0:1]
	s_movk_i32 s8, 0x10c0
	s_mul_hi_i32 s11, s14, 0x1100
	s_mul_i32 s10, s14, 0x1100
	v_ashrrev_i32_e32 v143, 6, v145
	v_cmp_gt_i32_e32 vcc, s8, v145
	s_waitcnt vmcnt(63) expcnt(7) lgkmcnt(15)
	s_barrier
	s_and_saveexec_b64 s[12:13], vcc
	s_cbranch_execz .LBB0_715
	s_waitcnt vmcnt(0)
	v_add_u32_e32 v168, s17, v143
	v_cmp_le_i32_e32 vcc, s15, v168
	v_cmp_gt_i32_e64 s[8:9], s16, v168
	s_and_b64 s[26:27], vcc, s[8:9]
	v_mov_b32_e32 v152, 0
	s_and_saveexec_b64 s[8:9], s[26:27]
	s_cbranch_execz .LBB0_714
	v_lshl_add_u64 v[4:5], s[10:11], 0, v[168:169]
	v_lshlrev_b64 v[4:5], 10, v[4:5]
	v_lshl_add_u64 v[4:5], v[2:3], 0, v[4:5]
	global_load_ushort v152, v[4:5], off

; DI float bf2f(u16 v) { return __uint_as_float(((unsigned)v) << 16); }
; DI void lru_job(const Params& P, int layer, int b, int chunk, int blk, int mode, char* smem, const LruConst& C) {
;     ...
;   for (int it = 0; it < 17; ++it) {
;     int idx = tid + it * 256;
;     int rr = idx >> 6, dd = idx & 63, pp = p0 - 1 + rr;
;     if (idx < 67 * 64) xs[idx] = (pp >= seg_lo && pp < seg_hi) ? bf2f(XA[((size_t)b * TB + pp) * 512 + blk * 64 + dd]) : 0.f;
;   }
.LBB0_715:
	s_or_b64 exec, exec, s[12:13]
	s_movk_i32 s8, 0xfc0
	v_cmp_gt_i32_e32 vcc, s8, v145
	s_and_saveexec_b64 s[12:13], vcc
	s_cbranch_execz .LBB0_719
	v_add_u32_e32 v1, 0x100, v145
	v_ashrrev_i32_e32 v1, 6, v1
	v_add_u32_e32 v168, s17, v1
	v_cmp_le_i32_e32 vcc, s15, v168
	v_cmp_gt_i32_e64 s[8:9], s16, v168
	s_and_b64 s[26:27], vcc, s[8:9]
	v_mov_b32_e32 v153, 0
	s_and_saveexec_b64 s[8:9], s[26:27]
	s_cbranch_execz .LBB0_718
	v_lshl_add_u64 v[4:5], s[10:11], 0, v[168:169]
	v_lshlrev_b64 v[4:5], 10, v[4:5]
	v_lshl_add_u64 v[4:5], v[2:3], 0, v[4:5]
	global_load_ushort v153, v[4:5], off

; DI float bf2f(u16 v) { return __uint_as_float(((unsigned)v) << 16); }
; DI void lru_job(const Params& P, int layer, int b, int chunk, int blk, int mode, char* smem, const LruConst& C) {
;     ...
;   for (int it = 0; it < 17; ++it) {
;     int idx = tid + it * 256;
;     int rr = idx >> 6, dd = idx & 63, pp = p0 - 1 + rr;
;     if (idx < 67 * 64) xs[idx] = (pp >= seg_lo && pp < seg_hi) ? bf2f(XA[((size_t)b * TB + pp) * 512 + blk * 64 + dd]) : 0.f;
;   }
.LBB0_719:
	s_or_b64 exec, exec, s[12:13]
	s_movk_i32 s8, 0xec0
	v_cmp_gt_i32_e32 vcc, s8, v145
	s_and_saveexec_b64 s[12:13], vcc
	s_cbranch_execz .LBB0_723
	v_add_u32_e32 v1, 0x200, v145
	v_ashrrev_i32_e32 v1, 6, v1
	v_add_u32_e32 v168, s17, v1
	v_cmp_le_i32_e32 vcc, s15, v168
	v_cmp_gt_i32_e64 s[8:9], s16, v168
	s_and_b64 s[26:27], vcc, s[8:9]
	v_mov_b32_e32 v154, 0
	s_and_saveexec_b64 s[8:9], s[26:27]
	s_cbranch_execz .LBB0_722
	v_lshl_add_u64 v[4:5], s[10:11], 0, v[168:169]
	v_lshlrev_b64 v[4:5], 10, v[4:5]
	v_lshl_add_u64 v[4:5], v[2:3], 0, v[4:5]
	global_load_ushort v154, v[4:5], off

; DI float bf2f(u16 v) { return __uint_as_float(((unsigned)v) << 16); }
; DI void lru_job(const Params& P, int layer, int b, int chunk, int blk, int mode, char* smem, const LruConst& C) {
;     ...
;   for (int it = 0; it < 17; ++it) {
;     int idx = tid + it * 256;
;     int rr = idx >> 6, dd = idx & 63, pp = p0 - 1 + rr;
;     if (idx < 67 * 64) xs[idx] = (pp >= seg_lo && pp < seg_hi) ? bf2f(XA[((size_t)b * TB + pp) * 512 + blk * 64 + dd]) : 0.f;
;   }
.LBB0_723:
	s_or_b64 exec, exec, s[12:13]
	s_movk_i32 s8, 0xdc0
	v_cmp_gt_i32_e32 vcc, s8, v145
	s_and_saveexec_b64 s[12:13], vcc
	s_cbranch_execz .LBB0_727
	v_add_u32_e32 v1, 0x300, v145
	v_ashrrev_i32_e32 v1, 6, v1
	v_add_u32_e32 v168, s17, v1
	v_cmp_le_i32_e32 vcc, s15, v168
	v_cmp_gt_i32_e64 s[8:9], s16, v168
	s_and_b64 s[26:27], vcc, s[8:9]
	v_mov_b32_e32 v155, 0
	s_and_saveexec_b64 s[8:9], s[26:27]
	s_cbranch_execz .LBB0_726
	v_lshl_add_u64 v[4:5], s[10:11], 0, v[168:169]
	v_lshlrev_b64 v[4:5], 10, v[4:5]
	v_lshl_add_u64 v[4:5], v[2:3], 0, v[4:5]
	global_load_ushort v155, v[4:5], off

; DI float bf2f(u16 v) { return __uint_as_float(((unsigned)v) << 16); }
; DI void lru_job(const Params& P, int layer, int b, int chunk, int blk, int mode, char* smem, const LruConst& C) {
;     ...
;   for (int it = 0; it < 17; ++it) {
;     int idx = tid + it * 256;
;     int rr = idx >> 6, dd = idx & 63, pp = p0 - 1 + rr;
;     if (idx < 67 * 64) xs[idx] = (pp >= seg_lo && pp < seg_hi) ? bf2f(XA[((size_t)b * TB + pp) * 512 + blk * 64 + dd]) : 0.f;
;   }
.LBB0_727:
	s_or_b64 exec, exec, s[12:13]
	s_movk_i32 s8, 0xcc0
	v_cmp_gt_i32_e32 vcc, s8, v145
	s_and_saveexec_b64 s[12:13], vcc
	s_cbranch_execz .LBB0_731
	v_add_u32_e32 v1, 0x400, v145
	v_ashrrev_i32_e32 v1, 6, v1
	v_add_u32_e32 v168, s17, v1
	v_cmp_le_i32_e32 vcc, s15, v168
	v_cmp_gt_i32_e64 s[8:9], s16, v168
	s_and_b64 s[26:27], vcc, s[8:9]
	v_mov_b32_e32 v156, 0
	s_and_saveexec_b64 s[8:9], s[26:27]
	s_cbranch_execz .LBB0_730
	v_lshl_add_u64 v[4:5], s[10:11], 0, v[168:169]
	v_lshlrev_b64 v[4:5], 10, v[4:5]
	v_lshl_add_u64 v[4:5], v[2:3], 0, v[4:5]
	global_load_ushort v156, v[4:5], off

; DI float bf2f(u16 v) { return __uint_as_float(((unsigned)v) << 16); }
; DI void lru_job(const Params& P, int layer, int b, int chunk, int blk, int mode, char* smem, const LruConst& C) {
;     ...
;   for (int it = 0; it < 17; ++it) {
;     int idx = tid + it * 256;
;     int rr = idx >> 6, dd = idx & 63, pp = p0 - 1 + rr;
;     if (idx < 67 * 64) xs[idx] = (pp >= seg_lo && pp < seg_hi) ? bf2f(XA[((size_t)b * TB + pp) * 512 + blk * 64 + dd]) : 0.f;
;   }
.LBB0_731:
	s_or_b64 exec, exec, s[12:13]
	s_movk_i32 s8, 0xbc0
	v_cmp_gt_i32_e32 vcc, s8, v145
	s_and_saveexec_b64 s[12:13], vcc
	s_cbranch_execz .LBB0_735
	v_add_u32_e32 v1, 0x500, v145
	v_ashrrev_i32_e32 v1, 6, v1
	v_add_u32_e32 v168, s17, v1
	v_cmp_le_i32_e32 vcc, s15, v168
	v_cmp_gt_i32_e64 s[8:9], s16, v168
	s_and_b64 s[26:27], vcc, s[8:9]
	v_mov_b32_e32 v157, 0
	s_and_saveexec_b64 s[8:9], s[26:27]
	s_cbranch_execz .LBB0_734
	v_lshl_add_u64 v[4:5], s[10:11], 0, v[168:169]
	v_lshlrev_b64 v[4:5], 10, v[4:5]
	v_lshl_add_u64 v[4:5], v[2:3], 0, v[4:5]
	global_load_ushort v157, v[4:5], off

; DI float bf2f(u16 v) { return __uint_as_float(((unsigned)v) << 16); }
; DI void lru_job(const Params& P, int layer, int b, int chunk, int blk, int mode, char* smem, const LruConst& C) {
;     ...
;   for (int it = 0; it < 17; ++it) {
;     int idx = tid + it * 256;
;     int rr = idx >> 6, dd = idx & 63, pp = p0 - 1 + rr;
;     if (idx < 67 * 64) xs[idx] = (pp >= seg_lo && pp < seg_hi) ? bf2f(XA[((size_t)b * TB + pp) * 512 + blk * 64 + dd]) : 0.f;
;   }
.LBB0_735:
	s_or_b64 exec, exec, s[12:13]
	s_movk_i32 s8, 0xac0
	v_cmp_gt_i32_e32 vcc, s8, v145
	s_and_saveexec_b64 s[12:13], vcc
	s_cbranch_execz .LBB0_739
	v_add_u32_e32 v1, 0x600, v145
	v_ashrrev_i32_e32 v1, 6, v1
	v_add_u32_e32 v168, s17, v1
	v_cmp_le_i32_e32 vcc, s15, v168
	v_cmp_gt_i32_e64 s[8:9], s16, v168
	s_and_b64 s[26:27], vcc, s[8:9]
	v_mov_b32_e32 v158, 0
	s_and_saveexec_b64 s[8:9], s[26:27]
	s_cbranch_execz .LBB0_738
	v_lshl_add_u64 v[4:5], s[10:11], 0, v[168:169]
	v_lshlrev_b64 v[4:5], 10, v[4:5]
	v_lshl_add_u64 v[4:5], v[2:3], 0, v[4:5]
	global_load_ushort v158, v[4:5], off

; DI float bf2f(u16 v) { return __uint_as_float(((unsigned)v) << 16); }
; DI void lru_job(const Params& P, int layer, int b, int chunk, int blk, int mode, char* smem, const LruConst& C) {
;     ...
;   for (int it = 0; it < 17; ++it) {
;     int idx = tid + it * 256;
;     int rr = idx >> 6, dd = idx & 63, pp = p0 - 1 + rr;
;     if (idx < 67 * 64) xs[idx] = (pp >= seg_lo && pp < seg_hi) ? bf2f(XA[((size_t)b * TB + pp) * 512 + blk * 64 + dd]) : 0.f;
;   }
.LBB0_739:
	s_or_b64 exec, exec, s[12:13]
	s_movk_i32 s8, 0x9c0
	v_cmp_gt_i32_e32 vcc, s8, v145
	s_and_saveexec_b64 s[12:13], vcc
	s_cbranch_execz .LBB0_743
	v_add_u32_e32 v1, 0x700, v145
	v_ashrrev_i32_e32 v1, 6, v1
	v_add_u32_e32 v168, s17, v1
	v_cmp_le_i32_e32 vcc, s15, v168
	v_cmp_gt_i32_e64 s[8:9], s16, v168
	s_and_b64 s[26:27], vcc, s[8:9]
	v_mov_b32_e32 v159, 0
	s_and_saveexec_b64 s[8:9], s[26:27]
	s_cbranch_execz .LBB0_742
	v_lshl_add_u64 v[4:5], s[10:11], 0, v[168:169]
	v_lshlrev_b64 v[4:5], 10, v[4:5]
	v_lshl_add_u64 v[4:5], v[2:3], 0, v[4:5]
	global_load_ushort v159, v[4:5], off

; DI float bf2f(u16 v) { return __uint_as_float(((unsigned)v) << 16); }
; DI void lru_job(const Params& P, int layer, int b, int chunk, int blk, int mode, char* smem, const LruConst& C) {
;     ...
;   for (int it = 0; it < 17; ++it) {
;     int idx = tid + it * 256;
;     int rr = idx >> 6, dd = idx & 63, pp = p0 - 1 + rr;
;     if (idx < 67 * 64) xs[idx] = (pp >= seg_lo && pp < seg_hi) ? bf2f(XA[((size_t)b * TB + pp) * 512 + blk * 64 + dd]) : 0.f;
;   }
.LBB0_743:
	s_or_b64 exec, exec, s[12:13]
	s_movk_i32 s8, 0x8c0
	v_cmp_gt_i32_e32 vcc, s8, v145
	s_and_saveexec_b64 s[12:13], vcc
	s_cbranch_execz .LBB0_747
	v_add_u32_e32 v1, 0x800, v145
	v_ashrrev_i32_e32 v1, 6, v1
	v_add_u32_e32 v168, s17, v1
	v_cmp_le_i32_e32 vcc, s15, v168
	v_cmp_gt_i32_e64 s[8:9], s16, v168
	s_and_b64 s[26:27], vcc, s[8:9]
	v_mov_b32_e32 v160, 0
	s_and_saveexec_b64 s[8:9], s[26:27]
	s_cbranch_execz .LBB0_746
	v_lshl_add_u64 v[4:5], s[10:11], 0, v[168:169]
	v_lshlrev_b64 v[4:5], 10, v[4:5]
	v_lshl_add_u64 v[4:5], v[2:3], 0, v[4:5]
	global_load_ushort v160, v[4:5], off

; DI float bf2f(u16 v) { return __uint_as_float(((unsigned)v) << 16); }
; DI void lru_job(const Params& P, int layer, int b, int chunk, int blk, int mode, char* smem, const LruConst& C) {
;     ...
;   for (int it = 0; it < 17; ++it) {
;     int idx = tid + it * 256;
;     int rr = idx >> 6, dd = idx & 63, pp = p0 - 1 + rr;
;     if (idx < 67 * 64) xs[idx] = (pp >= seg_lo && pp < seg_hi) ? bf2f(XA[((size_t)b * TB + pp) * 512 + blk * 64 + dd]) : 0.f;
;   }
.LBB0_747:
	s_or_b64 exec, exec, s[12:13]
	s_movk_i32 s8, 0x7c0
	v_cmp_gt_i32_e32 vcc, s8, v145
	s_and_saveexec_b64 s[12:13], vcc
	s_cbranch_execz .LBB0_751
	v_add_u32_e32 v1, 0x900, v145
	v_ashrrev_i32_e32 v1, 6, v1
	v_add_u32_e32 v168, s17, v1
	v_cmp_le_i32_e32 vcc, s15, v168
	v_cmp_gt_i32_e64 s[8:9], s16, v168
	s_and_b64 s[26:27], vcc, s[8:9]
	v_mov_b32_e32 v161, 0
	s_and_saveexec_b64 s[8:9], s[26:27]
	s_cbranch_execz .LBB0_750
	v_lshl_add_u64 v[4:5], s[10:11], 0, v[168:169]
	v_lshlrev_b64 v[4:5], 10, v[4:5]
	v_lshl_add_u64 v[4:5], v[2:3], 0, v[4:5]
	global_load_ushort v161, v[4:5], off

; DI float bf2f(u16 v) { return __uint_as_float(((unsigned)v) << 16); }
; DI void lru_job(const Params& P, int layer, int b, int chunk, int blk, int mode, char* smem, const LruConst& C) {
;     ...
;   for (int it = 0; it < 17; ++it) {
;     int idx = tid + it * 256;
;     int rr = idx >> 6, dd = idx & 63, pp = p0 - 1 + rr;
;     if (idx < 67 * 64) xs[idx] = (pp >= seg_lo && pp < seg_hi) ? bf2f(XA[((size_t)b * TB + pp) * 512 + blk * 64 + dd]) : 0.f;
;   }
.LBB0_751:
	s_or_b64 exec, exec, s[12:13]
	s_movk_i32 s8, 0x6c0
	v_cmp_gt_i32_e32 vcc, s8, v145
	s_and_saveexec_b64 s[12:13], vcc
	s_cbranch_execz .LBB0_755
	v_add_u32_e32 v1, 0xa00, v145
	v_ashrrev_i32_e32 v1, 6, v1
	v_add_u32_e32 v168, s17, v1
	v_cmp_le_i32_e32 vcc, s15, v168
	v_cmp_gt_i32_e64 s[8:9], s16, v168
	s_and_b64 s[26:27], vcc, s[8:9]
	v_mov_b32_e32 v162, 0
	s_and_saveexec_b64 s[8:9], s[26:27]
	s_cbranch_execz .LBB0_754
	v_lshl_add_u64 v[4:5], s[10:11], 0, v[168:169]
	v_lshlrev_b64 v[4:5], 10, v[4:5]
	v_lshl_add_u64 v[4:5], v[2:3], 0, v[4:5]
	global_load_ushort v162, v[4:5], off

; DI float bf2f(u16 v) { return __uint_as_float(((unsigned)v) << 16); }
; DI void lru_job(const Params& P, int layer, int b, int chunk, int blk, int mode, char* smem, const LruConst& C) {
;     ...
;   for (int it = 0; it < 17; ++it) {
;     int idx = tid + it * 256;
;     int rr = idx >> 6, dd = idx & 63, pp = p0 - 1 + rr;
;     if (idx < 67 * 64) xs[idx] = (pp >= seg_lo && pp < seg_hi) ? bf2f(XA[((size_t)b * TB + pp) * 512 + blk * 64 + dd]) : 0.f;
;   }
.LBB0_755:
	s_or_b64 exec, exec, s[12:13]
	s_movk_i32 s8, 0x5c0
	v_cmp_gt_i32_e32 vcc, s8, v145
	s_and_saveexec_b64 s[12:13], vcc
	s_cbranch_execz .LBB0_759
	v_add_u32_e32 v1, 0xb00, v145
	v_ashrrev_i32_e32 v1, 6, v1
	v_add_u32_e32 v168, s17, v1
	v_cmp_le_i32_e32 vcc, s15, v168
	v_cmp_gt_i32_e64 s[8:9], s16, v168
	s_and_b64 s[26:27], vcc, s[8:9]
	v_mov_b32_e32 v163, 0
	s_and_saveexec_b64 s[8:9], s[26:27]
	s_cbranch_execz .LBB0_758
	v_lshl_add_u64 v[4:5], s[10:11], 0, v[168:169]
	v_lshlrev_b64 v[4:5], 10, v[4:5]
	v_lshl_add_u64 v[4:5], v[2:3], 0, v[4:5]
	global_load_ushort v163, v[4:5], off

; DI float bf2f(u16 v) { return __uint_as_float(((unsigned)v) << 16); }
; DI void lru_job(const Params& P, int layer, int b, int chunk, int blk, int mode, char* smem, const LruConst& C) {
;     ...
;   for (int it = 0; it < 17; ++it) {
;     int idx = tid + it * 256;
;     int rr = idx >> 6, dd = idx & 63, pp = p0 - 1 + rr;
;     if (idx < 67 * 64) xs[idx] = (pp >= seg_lo && pp < seg_hi) ? bf2f(XA[((size_t)b * TB + pp) * 512 + blk * 64 + dd]) : 0.f;
;   }
.LBB0_759:
	s_or_b64 exec, exec, s[12:13]
	s_movk_i32 s8, 0x4c0
	v_cmp_gt_i32_e32 vcc, s8, v145
	s_and_saveexec_b64 s[12:13], vcc
	s_cbranch_execz .LBB0_763
	v_add_u32_e32 v1, 0xc00, v145
	v_ashrrev_i32_e32 v1, 6, v1
	v_add_u32_e32 v168, s17, v1
	v_cmp_le_i32_e32 vcc, s15, v168
	v_cmp_gt_i32_e64 s[8:9], s16, v168
	s_and_b64 s[26:27], vcc, s[8:9]
	v_mov_b32_e32 v164, 0
	s_and_saveexec_b64 s[8:9], s[26:27]
	s_cbranch_execz .LBB0_762
	v_lshl_add_u64 v[4:5], s[10:11], 0, v[168:169]
	v_lshlrev_b64 v[4:5], 10, v[4:5]
	v_lshl_add_u64 v[4:5], v[2:3], 0, v[4:5]
	global_load_ushort v164, v[4:5], off

; DI float bf2f(u16 v) { return __uint_as_float(((unsigned)v) << 16); }
; DI void lru_job(const Params& P, int layer, int b, int chunk, int blk, int mode, char* smem, const LruConst& C) {
;     ...
;   for (int it = 0; it < 17; ++it) {
;     int idx = tid + it * 256;
;     int rr = idx >> 6, dd = idx & 63, pp = p0 - 1 + rr;
;     if (idx < 67 * 64) xs[idx] = (pp >= seg_lo && pp < seg_hi) ? bf2f(XA[((size_t)b * TB + pp) * 512 + blk * 64 + dd]) : 0.f;
;   }
.LBB0_763:
	s_or_b64 exec, exec, s[12:13]
	s_movk_i32 s8, 0x3c0
	v_cmp_gt_i32_e32 vcc, s8, v145
	s_and_saveexec_b64 s[12:13], vcc
	s_cbranch_execz .LBB0_767
	v_add_u32_e32 v1, 0xd00, v145
	v_ashrrev_i32_e32 v1, 6, v1
	v_add_u32_e32 v168, s17, v1
	v_cmp_le_i32_e32 vcc, s15, v168
	v_cmp_gt_i32_e64 s[8:9], s16, v168
	s_and_b64 s[26:27], vcc, s[8:9]
	v_mov_b32_e32 v165, 0
	s_and_saveexec_b64 s[8:9], s[26:27]
	s_cbranch_execz .LBB0_766
	v_lshl_add_u64 v[4:5], s[10:11], 0, v[168:169]
	v_lshlrev_b64 v[4:5], 10, v[4:5]
	v_lshl_add_u64 v[4:5], v[2:3], 0, v[4:5]
	global_load_ushort v165, v[4:5], off

; DI float bf2f(u16 v) { return __uint_as_float(((unsigned)v) << 16); }
; DI void lru_job(const Params& P, int layer, int b, int chunk, int blk, int mode, char* smem, const LruConst& C) {
;     ...
;   for (int it = 0; it < 17; ++it) {
;     int idx = tid + it * 256;
;     int rr = idx >> 6, dd = idx & 63, pp = p0 - 1 + rr;
;     if (idx < 67 * 64) xs[idx] = (pp >= seg_lo && pp < seg_hi) ? bf2f(XA[((size_t)b * TB + pp) * 512 + blk * 64 + dd]) : 0.f;
;   }
.LBB0_767:
	s_or_b64 exec, exec, s[12:13]
	s_movk_i32 s8, 0x2c0
	v_cmp_gt_i32_e32 vcc, s8, v145
	s_and_saveexec_b64 s[12:13], vcc
	s_cbranch_execz .LBB0_771
	v_add_u32_e32 v1, 0xe00, v145
	v_ashrrev_i32_e32 v1, 6, v1
	v_add_u32_e32 v168, s17, v1
	v_cmp_le_i32_e32 vcc, s15, v168
	v_cmp_gt_i32_e64 s[8:9], s16, v168
	s_and_b64 s[26:27], vcc, s[8:9]
	v_mov_b32_e32 v166, 0
	s_and_saveexec_b64 s[8:9], s[26:27]
	s_cbranch_execz .LBB0_770
	v_lshl_add_u64 v[4:5], s[10:11], 0, v[168:169]
	v_lshlrev_b64 v[4:5], 10, v[4:5]
	v_lshl_add_u64 v[4:5], v[2:3], 0, v[4:5]
	global_load_ushort v166, v[4:5], off

; DI float bf2f(u16 v) { return __uint_as_float(((unsigned)v) << 16); }
; DI void lru_job(const Params& P, int layer, int b, int chunk, int blk, int mode, char* smem, const LruConst& C) {
;     ...
;   for (int it = 0; it < 17; ++it) {
;     int idx = tid + it * 256;
;     int rr = idx >> 6, dd = idx & 63, pp = p0 - 1 + rr;
;     if (idx < 67 * 64) xs[idx] = (pp >= seg_lo && pp < seg_hi) ? bf2f(XA[((size_t)b * TB + pp) * 512 + blk * 64 + dd]) : 0.f;
;   }
.LBB0_771:
	s_or_b64 exec, exec, s[12:13]
	s_movk_i32 s8, 0x1c0
	v_cmp_gt_i32_e32 vcc, s8, v145
	s_and_saveexec_b64 s[12:13], vcc
	s_cbranch_execz .LBB0_775
	v_add_u32_e32 v1, 0xf00, v145
	v_ashrrev_i32_e32 v1, 6, v1
	v_add_u32_e32 v168, s17, v1
	v_cmp_le_i32_e32 vcc, s15, v168
	v_cmp_gt_i32_e64 s[8:9], s16, v168
	s_and_b64 s[26:27], vcc, s[8:9]
	v_mov_b32_e32 v167, 0
	s_and_saveexec_b64 s[8:9], s[26:27]
	s_cbranch_execz .LBB0_774
	v_lshl_add_u64 v[4:5], s[10:11], 0, v[168:169]
	v_lshlrev_b64 v[4:5], 10, v[4:5]
	v_lshl_add_u64 v[4:5], v[2:3], 0, v[4:5]
	global_load_ushort v167, v[4:5], off

; DI float bf2f(u16 v) { return __uint_as_float(((unsigned)v) << 16); }
; DI void lru_job(const Params& P, int layer, int b, int chunk, int blk, int mode, char* smem, const LruConst& C) {
;     ...
;   for (int it = 0; it < 17; ++it) {
;     int idx = tid + it * 256;
;     int rr = idx >> 6, dd = idx & 63, pp = p0 - 1 + rr;
;     if (idx < 67 * 64) xs[idx] = (pp >= seg_lo && pp < seg_hi) ? bf2f(XA[((size_t)b * TB + pp) * 512 + blk * 64 + dd]) : 0.f;
;   }
.LBB0_775:
	s_or_b64 exec, exec, s[12:13]
	s_waitcnt vmcnt(0)
	v_lshlrev_b32_e32 v4, 2, v145
	v_lshlrev_b32_e32 v1, 16, v152
	ds_write_b32 v4, v1 offset:9216
	v_lshlrev_b32_e32 v1, 16, v153
	ds_write_b32 v4, v1 offset:10240
	v_lshlrev_b32_e32 v1, 16, v154
	ds_write_b32 v4, v1 offset:11264
	v_lshlrev_b32_e32 v1, 16, v155
	ds_write_b32 v4, v1 offset:12288
	v_lshlrev_b32_e32 v1, 16, v156
	ds_write_b32 v4, v1 offset:13312
	v_lshlrev_b32_e32 v1, 16, v157
	ds_write_b32 v4, v1 offset:14336
	v_lshlrev_b32_e32 v1, 16, v158
	ds_write_b32 v4, v1 offset:15360
	v_lshlrev_b32_e32 v1, 16, v159
	ds_write_b32 v4, v1 offset:16384
	v_lshlrev_b32_e32 v1, 16, v160
	ds_write_b32 v4, v1 offset:17408
	v_lshlrev_b32_e32 v1, 16, v161
	ds_write_b32 v4, v1 offset:18432
	v_lshlrev_b32_e32 v1, 16, v162
	ds_write_b32 v4, v1 offset:19456
	v_lshlrev_b32_e32 v1, 16, v163
	ds_write_b32 v4, v1 offset:20480
	v_lshlrev_b32_e32 v1, 16, v164
	ds_write_b32 v4, v1 offset:21504
	v_lshlrev_b32_e32 v1, 16, v165
	ds_write_b32 v4, v1 offset:22528
	v_lshlrev_b32_e32 v1, 16, v166
	ds_write_b32 v4, v1 offset:23552
	v_lshlrev_b32_e32 v1, 16, v167
	ds_write_b32 v4, v1 offset:24576
	s_movk_i32 s8, 0xc0
	v_cmp_gt_i32_e32 vcc, s8, v145
	s_and_saveexec_b64 s[12:13], vcc
	s_cbranch_execz .LBB0_779
	v_add_u32_e32 v1, 0x1000, v145
	v_ashrrev_i32_e32 v1, 6, v1
	s_waitcnt vmcnt(0)
	v_add_u32_e32 v168, s17, v1
	v_cmp_le_i32_e32 vcc, s15, v168
	v_cmp_gt_i32_e64 s[8:9], s16, v168
	s_and_b64 s[16:17], vcc, s[8:9]
	v_mov_b32_e32 v1, 0
	s_and_saveexec_b64 s[8:9], s[16:17]
	s_cbranch_execz .LBB0_778
	v_lshl_add_u64 v[4:5], s[10:11], 0, v[168:169]
	v_lshlrev_b64 v[4:5], 10, v[4:5]
	v_lshl_add_u64 v[2:3], v[2:3], 0, v[4:5]
	global_load_ushort v1, v[2:3], off
	s_waitcnt vmcnt(0)
	v_lshlrev_b32_e32 v1, 16, v1
